# P3 carries: S5 chain on wave 0 of every block and RG-LRU chain on wave 1 of 64 blocks, loads prefetched 3 batches ahead (ring of 4 register sets)
# speedup vs baseline: 1.0398x; 1.0103x over previous
; __device__ __forceinline__ void phase_carry(Frame& F, const Params& p) {
;     if (F.bx < 32) {
;         const int id = F.bx * NTHREADS + F.tid, pp = id & 63, d = (id >> 6) & 1, g = (id >> 7) & 63, b = id >> 13;
;     ...
;     } else if (F.bx < 40) {
;         const int id = (F.bx - 32) * NTHREADS + F.tid, ch = id & 1023, d = (id >> 10) & 1, b = id >> 11;
.LBB0_768:
	s_or_b64 exec, exec, s[4:5]
	s_waitcnt lgkmcnt(0)
	s_barrier
	v_mbcnt_lo_u32_b32 v8, -1, 0
	v_mbcnt_hi_u32_b32 v8, -1, v8
	s_lshl_b32 s4, s2, 6
	v_add_u32_e32 v9, s4, v8
	s_cmp_eq_u32 s3, 0
	s_cbranch_scc1 .LBB0_792
	s_cmp_lg_u32 s3, 64
	s_cbranch_scc1 .LBB0_770
	s_cmp_gt_u32 s2, 63
	s_cbranch_scc1 .LBB0_770
	s_branch .Lmy_lru

; __device__ __forceinline__ void phase_carry(Frame& F, const Params& p) {
;     ...
;         const int id = (F.bx - 32) * NTHREADS + F.tid, ch = id & 1023, d = (id >> 10) & 1, b = id >> 11;
;         const float* PL = (const float*)(F.ws + WS_PL) + ((size_t)(b * 2 + d) * NQ * 1024 + ch) * 2;
;         float* LC = (float*)(F.ws + WS_LC) + (size_t)(b * 2 + d) * NQ * 1024 + ch;
;         float h = 0.f;
;         if (d == 0) {
;             for (int q = 0; q < 8; ++q) { h = PL[(size_t)q * 2048] * h + PL[(size_t)q * 2048 + 1]; }
;             for (int q0 = 8; q0 < NQ; q0 += 8) {
;                 float P[8], L[8];
; #pragma unroll
;                 for (int u = 0; u < 8; ++u) { P[u] = PL[(size_t)(q0 + u) * 2048]; L[u] = PL[(size_t)(q0 + u) * 2048 + 1]; }
; #pragma unroll
;                 for (int u = 0; u < 8; ++u) { LC[(size_t)(q0 + u) * 1024] = h; h = P[u] * h + L[u]; }
;             }
;         } else {
;             for (int q = 7; q >= 0; --q) { h = PL[(size_t)q * 2048] * h + PL[(size_t)q * 2048 + 1]; }
;             for (int q0 = NQ - 8; q0 >= 8; q0 -= 8) {
;                 float P[8], L[8];
; #pragma unroll
;                 for (int u = 0; u < 8; ++u) { P[u] = PL[(size_t)(q0 + u) * 2048]; L[u] = PL[(size_t)(q0 + u) * 2048 + 1]; }
; #pragma unroll
;                 for (int u = 7; u >= 0; --u) { LC[(size_t)(q0 + u) * 1024] = h; h = P[u] * h + L[u]; }
.Lmy_lru:
	v_mov_b32_e32 v6, v9
	v_bfe_u32 v0, v6, 10, 1
	v_ashrrev_i32_e32 v1, 10, v6
	s_mov_b32 s4, 0xfffffe
	v_and_or_b32 v0, v1, s4, v0
	v_mul_i32_i24_e32 v2, 0x208, v0
	v_ashrrev_i32_e32 v3, 31, v2
	v_and_b32_e32 v10, 0x3ff, v6
	v_lshlrev_b64 v[0:1], 13, v[2:3]
	v_lshl_or_b32 v0, v10, 3, v0
	v_lshl_add_u64 v[4:5], s[56:57], 0, v[0:1]
	s_mov_b64 s[4:5], 0x14000000
	v_and_b32_e32 v6, 0x400, v6
	s_movk_i32 s10, 0x208
	v_lshl_add_u64 v[4:5], v[4:5], 0, s[4:5]
	v_cmp_ne_u32_e32 vcc, 0, v6
	v_lshlrev_b64 v[2:3], 12, v[2:3]
	s_and_saveexec_b64 s[4:5], vcc
	s_xor_b64 s[4:5], exec, s[4:5]
	s_cbranch_execz .LBB0_787
	v_add_co_u32_e32 v6, vcc, 0xe000, v4
	s_movk_i32 s6, 0x8000
	s_nop 0
	v_addc_co_u32_e32 v7, vcc, 0, v5, vcc
	v_add_co_u32_e32 v12, vcc, 0xc000, v4
	s_mov_b32 s8, 0xffff0000
	s_nop 0
	v_addc_co_u32_e32 v13, vcc, 0, v5, vcc
	v_add_co_u32_e32 v14, vcc, 0xa000, v4
	v_lshl_or_b32 v2, v10, 2, v2
	s_nop 0
	v_addc_co_u32_e32 v15, vcc, 0, v5, vcc
	v_add_co_u32_e32 v16, vcc, 0x8000, v4
	s_mov_b32 s7, -1
	s_nop 0
	v_addc_co_u32_e32 v17, vcc, 0, v5, vcc
	global_load_dwordx2 v[18:19], v[6:7], off
	s_nop 0
	global_load_dwordx2 v[12:13], v[12:13], off
	s_nop 0
	global_load_dwordx2 v[14:15], v[14:15], off
	s_nop 0
	global_load_dwordx2 v[16:17], v[16:17], off
	v_add_co_u32_e32 v6, vcc, 0x6000, v4
	s_mov_b32 s9, -1
	s_nop 0
	v_addc_co_u32_e32 v7, vcc, 0, v5, vcc
	v_add_co_u32_e32 v20, vcc, 0x4000, v4
	s_waitcnt vmcnt(3)
	v_fmac_f32_e32 v19, 0, v18
	v_addc_co_u32_e32 v21, vcc, 0, v5, vcc
	v_add_co_u32_e32 v22, vcc, 0x2000, v4
	s_waitcnt vmcnt(2)
	v_fmac_f32_e32 v13, v19, v12
	v_addc_co_u32_e32 v23, vcc, 0, v5, vcc
	global_load_dwordx2 v[24:25], v[6:7], off
	s_nop 0
	global_load_dwordx2 v[20:21], v[20:21], off
	s_nop 0
	global_load_dwordx2 v[22:23], v[22:23], off
	s_nop 0
	global_load_dwordx2 v[6:7], v[4:5], off
	s_waitcnt vmcnt(5)
	v_fmac_f32_e32 v15, v13, v14
	s_waitcnt vmcnt(4)
	v_fmac_f32_e32 v17, v15, v16
	s_waitcnt vmcnt(3)
	v_fmac_f32_e32 v25, v17, v24
	s_waitcnt vmcnt(2)
	v_fmac_f32_e32 v21, v25, v20
	s_waitcnt vmcnt(1)
	v_fmac_f32_e32 v23, v21, v22
	s_waitcnt vmcnt(0)
	v_fmac_f32_e32 v7, v23, v6
.LBB0_786:
	v_mov_b32_e32 v4, v7
	s_branch .Lmy_lru_d1

; __device__ __forceinline__ void phase_carry(Frame& F, const Params& p) {
;     ...
;             for (int q0 = 8; q0 < NQ; q0 += 8) {
;                 float P[8], L[8];
; #pragma unroll
;                 for (int u = 0; u < 8; ++u) { P[u] = PL[(size_t)(q0 + u) * 2048]; L[u] = PL[(size_t)(q0 + u) * 2048 + 1]; }
; #pragma unroll
;                 for (int u = 0; u < 8; ++u) { LC[(size_t)(q0 + u) * 1024] = h; h = P[u] * h + L[u]; }
;             }
.LBB0_789:
	v_mov_b32_e32 v4, v5
	s_branch .Lmy_lru_d0
.Lmy_lru_d0:
	s_mov_b32 s17, 8
	s_lshl_b32 s18, s17, 13
	s_add_u32 s4, s56, s18
	s_addc_u32 s5, s57, 0
	s_add_u32 s4, s4, 0x14000000
	s_addc_u32 s5, s5, 0
	s_lshl_b32 s18, s17, 12
	s_add_u32 s8, s56, s18
	s_addc_u32 s9, s57, 0
	s_add_u32 s8, s8, 0x15200000
	s_addc_u32 s9, s9, 0
	global_load_dwordx2 v[12:13], v0, s[4:5]
	s_add_u32 s4, s4, 0x2000
	s_addc_u32 s5, s5, 0
	global_load_dwordx2 v[14:15], v0, s[4:5]
	s_add_u32 s4, s4, 0x2000
	s_addc_u32 s5, s5, 0
	global_load_dwordx2 v[16:17], v0, s[4:5]
	s_add_u32 s4, s4, 0x2000
	s_addc_u32 s5, s5, 0
	global_load_dwordx2 v[18:19], v0, s[4:5]
	s_add_u32 s4, s4, 0x2000
	s_addc_u32 s5, s5, 0
	global_load_dword v10, v0, s[4:5]
	global_load_dword v10, v0, s[4:5]
	global_load_dword v10, v0, s[4:5]
	global_load_dword v10, v0, s[4:5]
	global_load_dwordx2 v[20:21], v0, s[4:5]
	s_add_u32 s4, s4, 0x2000
	s_addc_u32 s5, s5, 0
	global_load_dwordx2 v[22:23], v0, s[4:5]
	s_add_u32 s4, s4, 0x2000
	s_addc_u32 s5, s5, 0
	global_load_dwordx2 v[24:25], v0, s[4:5]
	s_add_u32 s4, s4, 0x2000
	s_addc_u32 s5, s5, 0
	global_load_dwordx2 v[26:27], v0, s[4:5]
	s_add_u32 s4, s4, 0x2000
	s_addc_u32 s5, s5, 0
	global_load_dword v10, v0, s[4:5]
	global_load_dword v10, v0, s[4:5]
	global_load_dword v10, v0, s[4:5]
	global_load_dword v10, v0, s[4:5]
	global_load_dwordx2 v[28:29], v0, s[4:5]
	s_add_u32 s4, s4, 0x2000
	s_addc_u32 s5, s5, 0
	global_load_dwordx2 v[30:31], v0, s[4:5]
	s_add_u32 s4, s4, 0x2000
	s_addc_u32 s5, s5, 0
	global_load_dwordx2 v[32:33], v0, s[4:5]
	s_add_u32 s4, s4, 0x2000
	s_addc_u32 s5, s5, 0
	global_load_dwordx2 v[34:35], v0, s[4:5]
	s_add_u32 s4, s4, 0x2000
	s_addc_u32 s5, s5, 0
	global_load_dword v10, v0, s[4:5]
	global_load_dword v10, v0, s[4:5]
	global_load_dword v10, v0, s[4:5]
	global_load_dword v10, v0, s[4:5]
	s_mov_b32 s12, 32
.Lmy_lrb_d0:
	global_load_dwordx2 v[36:37], v0, s[4:5]
	s_add_u32 s4, s4, 0x2000
	s_addc_u32 s5, s5, 0
	global_load_dwordx2 v[38:39], v0, s[4:5]
	s_add_u32 s4, s4, 0x2000
	s_addc_u32 s5, s5, 0
	global_load_dwordx2 v[40:41], v0, s[4:5]
	s_add_u32 s4, s4, 0x2000
	s_addc_u32 s5, s5, 0
	global_load_dwordx2 v[42:43], v0, s[4:5]
	s_add_u32 s4, s4, 0x2000
	s_addc_u32 s5, s5, 0
	s_waitcnt vmcnt(24)
	global_store_dword v2, v4, s[8:9]
	s_add_u32 s8, s8, 0x1000
	s_addc_u32 s9, s9, 0
	v_fma_f32 v5, v4, v12, v13
	global_store_dword v2, v5, s[8:9]
	s_add_u32 s8, s8, 0x1000
	s_addc_u32 s9, s9, 0
	v_fma_f32 v4, v5, v14, v15
	global_store_dword v2, v4, s[8:9]
	s_add_u32 s8, s8, 0x1000
	s_addc_u32 s9, s9, 0
	v_fma_f32 v5, v4, v16, v17
	global_store_dword v2, v5, s[8:9]
	s_add_u32 s8, s8, 0x1000
	s_addc_u32 s9, s9, 0
	v_fma_f32 v4, v5, v18, v19
	global_load_dwordx2 v[12:13], v0, s[4:5]
	s_add_u32 s4, s4, 0x2000
	s_addc_u32 s5, s5, 0
	global_load_dwordx2 v[14:15], v0, s[4:5]
	s_add_u32 s4, s4, 0x2000
	s_addc_u32 s5, s5, 0
	global_load_dwordx2 v[16:17], v0, s[4:5]
	s_add_u32 s4, s4, 0x2000
	s_addc_u32 s5, s5, 0
	global_load_dwordx2 v[18:19], v0, s[4:5]
	s_add_u32 s4, s4, 0x2000
	s_addc_u32 s5, s5, 0
	s_waitcnt vmcnt(24)
	global_store_dword v2, v4, s[8:9]
	s_add_u32 s8, s8, 0x1000
	s_addc_u32 s9, s9, 0
	v_fma_f32 v5, v4, v20, v21
	global_store_dword v2, v5, s[8:9]
	s_add_u32 s8, s8, 0x1000
	s_addc_u32 s9, s9, 0
	v_fma_f32 v4, v5, v22, v23
	global_store_dword v2, v4, s[8:9]
	s_add_u32 s8, s8, 0x1000
	s_addc_u32 s9, s9, 0
	v_fma_f32 v5, v4, v24, v25
	global_store_dword v2, v5, s[8:9]
	s_add_u32 s8, s8, 0x1000
	s_addc_u32 s9, s9, 0
	v_fma_f32 v4, v5, v26, v27
	global_load_dwordx2 v[20:21], v0, s[4:5]
	s_add_u32 s4, s4, 0x2000
	s_addc_u32 s5, s5, 0
	global_load_dwordx2 v[22:23], v0, s[4:5]
	s_add_u32 s4, s4, 0x2000
	s_addc_u32 s5, s5, 0
	global_load_dwordx2 v[24:25], v0, s[4:5]
	s_add_u32 s4, s4, 0x2000
	s_addc_u32 s5, s5, 0
	global_load_dwordx2 v[26:27], v0, s[4:5]
	s_add_u32 s4, s4, 0x2000
	s_addc_u32 s5, s5, 0
	s_waitcnt vmcnt(24)
	global_store_dword v2, v4, s[8:9]
	s_add_u32 s8, s8, 0x1000
	s_addc_u32 s9, s9, 0
	v_fma_f32 v5, v4, v28, v29
	global_store_dword v2, v5, s[8:9]
	s_add_u32 s8, s8, 0x1000
	s_addc_u32 s9, s9, 0
	v_fma_f32 v4, v5, v30, v31
	global_store_dword v2, v4, s[8:9]
	s_add_u32 s8, s8, 0x1000
	s_addc_u32 s9, s9, 0
	v_fma_f32 v5, v4, v32, v33
	global_store_dword v2, v5, s[8:9]
	s_add_u32 s8, s8, 0x1000
	s_addc_u32 s9, s9, 0
	v_fma_f32 v4, v5, v34, v35
	global_load_dwordx2 v[28:29], v0, s[4:5]
	s_add_u32 s4, s4, 0x2000
	s_addc_u32 s5, s5, 0
	global_load_dwordx2 v[30:31], v0, s[4:5]
	s_add_u32 s4, s4, 0x2000
	s_addc_u32 s5, s5, 0
	global_load_dwordx2 v[32:33], v0, s[4:5]
	s_add_u32 s4, s4, 0x2000
	s_addc_u32 s5, s5, 0
	global_load_dwordx2 v[34:35], v0, s[4:5]
	s_add_u32 s4, s4, 0x2000
	s_addc_u32 s5, s5, 0
	s_waitcnt vmcnt(24)
	global_store_dword v2, v4, s[8:9]
	s_add_u32 s8, s8, 0x1000
	s_addc_u32 s9, s9, 0
	v_fma_f32 v5, v4, v36, v37
	global_store_dword v2, v5, s[8:9]
	s_add_u32 s8, s8, 0x1000
	s_addc_u32 s9, s9, 0
	v_fma_f32 v4, v5, v38, v39
	global_store_dword v2, v4, s[8:9]
	s_add_u32 s8, s8, 0x1000
	s_addc_u32 s9, s9, 0
	v_fma_f32 v5, v4, v40, v41
	global_store_dword v2, v5, s[8:9]
	s_add_u32 s8, s8, 0x1000
	s_addc_u32 s9, s9, 0
	v_fma_f32 v4, v5, v42, v43
	s_sub_u32 s12, s12, 1
	s_cmp_lg_u32 s12, 0
	s_cbranch_scc1 .Lmy_lrb_d0
	s_waitcnt vmcnt(0)
	s_branch .Lmy_lru_out
; __device__ __forceinline__ void phase_carry(Frame& F, const Params& p) {
;     ...
;             for (int q = 7; q >= 0; --q) { h = PL[(size_t)q * 2048] * h + PL[(size_t)q * 2048 + 1]; }
;             for (int q0 = NQ - 8; q0 >= 8; q0 -= 8) {
;                 float P[8], L[8];
; #pragma unroll
;                 for (int u = 0; u < 8; ++u) { P[u] = PL[(size_t)(q0 + u) * 2048]; L[u] = PL[(size_t)(q0 + u) * 2048 + 1]; }
; #pragma unroll
;                 for (int u = 7; u >= 0; --u) { LC[(size_t)(q0 + u) * 1024] = h; h = P[u] * h + L[u]; }
;             }
.Lmy_lru_d1:
	s_mov_b32 s17, 0x207
	s_lshl_b32 s18, s17, 13
	s_add_u32 s4, s56, s18
	s_addc_u32 s5, s57, 0
	s_add_u32 s4, s4, 0x14000000
	s_addc_u32 s5, s5, 0
	s_lshl_b32 s18, s17, 12
	s_add_u32 s8, s56, s18
	s_addc_u32 s9, s57, 0
	s_add_u32 s8, s8, 0x15200000
	s_addc_u32 s9, s9, 0
	global_load_dwordx2 v[12:13], v0, s[4:5]
	s_add_u32 s4, s4, 0xffffe000
	s_addc_u32 s5, s5, -1
	global_load_dwordx2 v[14:15], v0, s[4:5]
	s_add_u32 s4, s4, 0xffffe000
	s_addc_u32 s5, s5, -1
	global_load_dwordx2 v[16:17], v0, s[4:5]
	s_add_u32 s4, s4, 0xffffe000
	s_addc_u32 s5, s5, -1
	global_load_dwordx2 v[18:19], v0, s[4:5]
	s_add_u32 s4, s4, 0xffffe000
	s_addc_u32 s5, s5, -1
	global_load_dword v10, v0, s[4:5]
	global_load_dword v10, v0, s[4:5]
	global_load_dword v10, v0, s[4:5]
	global_load_dword v10, v0, s[4:5]
	global_load_dwordx2 v[20:21], v0, s[4:5]
	s_add_u32 s4, s4, 0xffffe000
	s_addc_u32 s5, s5, -1
	global_load_dwordx2 v[22:23], v0, s[4:5]
	s_add_u32 s4, s4, 0xffffe000
	s_addc_u32 s5, s5, -1
	global_load_dwordx2 v[24:25], v0, s[4:5]
	s_add_u32 s4, s4, 0xffffe000
	s_addc_u32 s5, s5, -1
	global_load_dwordx2 v[26:27], v0, s[4:5]
	s_add_u32 s4, s4, 0xffffe000
	s_addc_u32 s5, s5, -1
	global_load_dword v10, v0, s[4:5]
	global_load_dword v10, v0, s[4:5]
	global_load_dword v10, v0, s[4:5]
	global_load_dword v10, v0, s[4:5]
	global_load_dwordx2 v[28:29], v0, s[4:5]
	s_add_u32 s4, s4, 0xffffe000
	s_addc_u32 s5, s5, -1
	global_load_dwordx2 v[30:31], v0, s[4:5]
	s_add_u32 s4, s4, 0xffffe000
	s_addc_u32 s5, s5, -1
	global_load_dwordx2 v[32:33], v0, s[4:5]
	s_add_u32 s4, s4, 0xffffe000
	s_addc_u32 s5, s5, -1
	global_load_dwordx2 v[34:35], v0, s[4:5]
	s_add_u32 s4, s4, 0xffffe000
	s_addc_u32 s5, s5, -1
	global_load_dword v10, v0, s[4:5]
	global_load_dword v10, v0, s[4:5]
	global_load_dword v10, v0, s[4:5]
	global_load_dword v10, v0, s[4:5]
	s_mov_b32 s12, 32
.Lmy_lrb_d1:
	global_load_dwordx2 v[36:37], v0, s[4:5]
	s_add_u32 s4, s4, 0xffffe000
	s_addc_u32 s5, s5, -1
	global_load_dwordx2 v[38:39], v0, s[4:5]
	s_add_u32 s4, s4, 0xffffe000
	s_addc_u32 s5, s5, -1
	global_load_dwordx2 v[40:41], v0, s[4:5]
	s_add_u32 s4, s4, 0xffffe000
	s_addc_u32 s5, s5, -1
	global_load_dwordx2 v[42:43], v0, s[4:5]
	s_add_u32 s4, s4, 0xffffe000
	s_addc_u32 s5, s5, -1
	s_waitcnt vmcnt(24)
	global_store_dword v2, v4, s[8:9]
	s_add_u32 s8, s8, 0xfffff000
	s_addc_u32 s9, s9, -1
	v_fma_f32 v5, v4, v12, v13
	global_store_dword v2, v5, s[8:9]
	s_add_u32 s8, s8, 0xfffff000
	s_addc_u32 s9, s9, -1
	v_fma_f32 v4, v5, v14, v15
	global_store_dword v2, v4, s[8:9]
	s_add_u32 s8, s8, 0xfffff000
	s_addc_u32 s9, s9, -1
	v_fma_f32 v5, v4, v16, v17
	global_store_dword v2, v5, s[8:9]
	s_add_u32 s8, s8, 0xfffff000
	s_addc_u32 s9, s9, -1
	v_fma_f32 v4, v5, v18, v19
	global_load_dwordx2 v[12:13], v0, s[4:5]
	s_add_u32 s4, s4, 0xffffe000
	s_addc_u32 s5, s5, -1
	global_load_dwordx2 v[14:15], v0, s[4:5]
	s_add_u32 s4, s4, 0xffffe000
	s_addc_u32 s5, s5, -1
	global_load_dwordx2 v[16:17], v0, s[4:5]
	s_add_u32 s4, s4, 0xffffe000
	s_addc_u32 s5, s5, -1
	global_load_dwordx2 v[18:19], v0, s[4:5]
	s_add_u32 s4, s4, 0xffffe000
	s_addc_u32 s5, s5, -1
	s_waitcnt vmcnt(24)
	global_store_dword v2, v4, s[8:9]
	s_add_u32 s8, s8, 0xfffff000
	s_addc_u32 s9, s9, -1
	v_fma_f32 v5, v4, v20, v21
	global_store_dword v2, v5, s[8:9]
	s_add_u32 s8, s8, 0xfffff000
	s_addc_u32 s9, s9, -1
	v_fma_f32 v4, v5, v22, v23
	global_store_dword v2, v4, s[8:9]
	s_add_u32 s8, s8, 0xfffff000
	s_addc_u32 s9, s9, -1
	v_fma_f32 v5, v4, v24, v25
	global_store_dword v2, v5, s[8:9]
	s_add_u32 s8, s8, 0xfffff000
	s_addc_u32 s9, s9, -1
	v_fma_f32 v4, v5, v26, v27
	global_load_dwordx2 v[20:21], v0, s[4:5]
	s_add_u32 s4, s4, 0xffffe000
	s_addc_u32 s5, s5, -1
	global_load_dwordx2 v[22:23], v0, s[4:5]
	s_add_u32 s4, s4, 0xffffe000
	s_addc_u32 s5, s5, -1
	global_load_dwordx2 v[24:25], v0, s[4:5]
	s_add_u32 s4, s4, 0xffffe000
	s_addc_u32 s5, s5, -1
	global_load_dwordx2 v[26:27], v0, s[4:5]
	s_add_u32 s4, s4, 0xffffe000
	s_addc_u32 s5, s5, -1
	s_waitcnt vmcnt(24)
	global_store_dword v2, v4, s[8:9]
	s_add_u32 s8, s8, 0xfffff000
	s_addc_u32 s9, s9, -1
	v_fma_f32 v5, v4, v28, v29
	global_store_dword v2, v5, s[8:9]
	s_add_u32 s8, s8, 0xfffff000
	s_addc_u32 s9, s9, -1
	v_fma_f32 v4, v5, v30, v31
	global_store_dword v2, v4, s[8:9]
	s_add_u32 s8, s8, 0xfffff000
	s_addc_u32 s9, s9, -1
	v_fma_f32 v5, v4, v32, v33
	global_store_dword v2, v5, s[8:9]
	s_add_u32 s8, s8, 0xfffff000
	s_addc_u32 s9, s9, -1
	v_fma_f32 v4, v5, v34, v35
	global_load_dwordx2 v[28:29], v0, s[4:5]
	s_add_u32 s4, s4, 0xffffe000
	s_addc_u32 s5, s5, -1
	global_load_dwordx2 v[30:31], v0, s[4:5]
	s_add_u32 s4, s4, 0xffffe000
	s_addc_u32 s5, s5, -1
	global_load_dwordx2 v[32:33], v0, s[4:5]
	s_add_u32 s4, s4, 0xffffe000
	s_addc_u32 s5, s5, -1
	global_load_dwordx2 v[34:35], v0, s[4:5]
	s_add_u32 s4, s4, 0xffffe000
	s_addc_u32 s5, s5, -1
	s_waitcnt vmcnt(24)
	global_store_dword v2, v4, s[8:9]
	s_add_u32 s8, s8, 0xfffff000
	s_addc_u32 s9, s9, -1
	v_fma_f32 v5, v4, v36, v37
	global_store_dword v2, v5, s[8:9]
	s_add_u32 s8, s8, 0xfffff000
	s_addc_u32 s9, s9, -1
	v_fma_f32 v4, v5, v38, v39
	global_store_dword v2, v4, s[8:9]
	s_add_u32 s8, s8, 0xfffff000
	s_addc_u32 s9, s9, -1
	v_fma_f32 v5, v4, v40, v41
	global_store_dword v2, v5, s[8:9]
	s_add_u32 s8, s8, 0xfffff000
	s_addc_u32 s9, s9, -1
	v_fma_f32 v4, v5, v42, v43
	s_sub_u32 s12, s12, 1
	s_cmp_lg_u32 s12, 0
	s_cbranch_scc1 .Lmy_lrb_d1
	s_waitcnt vmcnt(0)
	s_branch .Lmy_lru_out
.Lmy_lru_out:
	s_mov_b64 exec, -1
	s_branch .LBB0_770

; __device__ __forceinline__ void phase_carry(Frame& F, const Params& p) {
;     ...
;         const int id = F.bx * NTHREADS + F.tid, pp = id & 63, d = (id >> 6) & 1, g = (id >> 7) & 63, b = id >> 13;
;         const float lr = p.in[8][(d * 64 + g) * 64 + pp], li = p.in[9][(d * 64 + g) * 64 + pp], dt = __expf(p.in[10][d * 64 + g]);
;         const float mag = expf(32.f * dt * lr); float sn, cs; sincosf(32.f * dt * li, &sn, &cs); const float ar = mag * cs, ai = mag * sn;
.LBB0_792:
	s_load_dwordx2 s[4:5], s[0:1], 0x50
	v_mov_b32_e32 v1, v9
	v_bfe_u32 v10, v9, 6, 1
	v_bfe_u32 v4, v1, 7, 6
	v_lshl_or_b32 v0, v10, 6, v4
	v_lshlrev_b32_e32 v2, 2, v0
	s_waitcnt lgkmcnt(0)
	global_load_dword v3, v2, s[4:5]
	s_load_dwordx4 s[4:7], s[0:1], 0x40
	v_and_b32_e32 v8, 63, v8
	v_lshlrev_b32_e32 v2, 2, v8
	v_lshl_or_b32 v0, v0, 8, v2
	s_waitcnt lgkmcnt(0)
	global_load_dword v7, v0, s[6:7]
	global_load_dword v5, v0, s[4:5]
	s_brev_b32 s4, 18
	s_waitcnt vmcnt(2)
	v_mul_f32_e32 v0, 0x3fb8aa3b, v3
	v_exp_f32_e32 v0, v0
	s_nop 0
	v_mul_f32_e32 v6, 0x42000000, v0
	s_waitcnt vmcnt(1)
	v_mul_f32_e32 v0, v7, v6
	v_and_b32_e32 v3, 0x7fffffff, v0
	v_cmp_nlt_f32_e64 s[4:5], |v0|, s4
	s_and_saveexec_b64 s[6:7], s[4:5]
	s_xor_b64 s[10:11], exec, s[6:7]
	s_cbranch_execz .LBB0_794
	v_lshrrev_b32_e32 v7, 23, v3
	v_add_u32_e32 v7, 0xffffff88, v7
	v_not_b32_e32 v11, 63
	v_cmp_lt_u32_e32 vcc, 63, v7
	s_mov_b32 s8, 0xfe5163ab
	v_mov_b32_e32 v15, 0
	v_cndmask_b32_e32 v11, 0, v11, vcc
	v_add_u32_e32 v7, v11, v7
	v_not_b32_e32 v11, 31
	v_cmp_lt_u32_e64 s[4:5], 31, v7
	s_nop 1
	v_cndmask_b32_e64 v12, 0, v11, s[4:5]
	v_add_u32_e32 v7, v12, v7
	v_cmp_lt_u32_e64 s[6:7], 31, v7
	s_nop 1
	v_cndmask_b32_e64 v11, 0, v11, s[6:7]
	v_add_u32_e32 v7, v11, v7
	v_and_b32_e32 v11, 0x7fffff, v3
	v_or_b32_e32 v11, 0x800000, v11
	v_mad_u64_u32 v[12:13], s[8:9], v11, s8, 0
	v_mov_b32_e32 v14, v13
	s_mov_b32 s8, 0x3c439041
	v_mad_u64_u32 v[16:17], s[8:9], v11, s8, v[14:15]
	v_mov_b32_e32 v14, v17
	s_mov_b32 s8, 0xdb629599
	v_mad_u64_u32 v[18:19], s[8:9], v11, s8, v[14:15]
	v_mov_b32_e32 v14, v19
	s_mov_b32 s8, 0xf534ddc0
	v_mad_u64_u32 v[20:21], s[8:9], v11, s8, v[14:15]
	v_mov_b32_e32 v14, v21
	s_mov_b32 s8, 0xfc2757d1
	v_mad_u64_u32 v[22:23], s[8:9], v11, s8, v[14:15]
	v_mov_b32_e32 v14, v23
	s_mov_b32 s8, 0x4e441529
	v_mad_u64_u32 v[24:25], s[8:9], v11, s8, v[14:15]
	v_mov_b32_e32 v14, v25
	s_mov_b32 s8, 0xa2f9836e
	v_mad_u64_u32 v[14:15], s[8:9], v11, s8, v[14:15]
	v_cndmask_b32_e32 v13, v24, v20, vcc
	v_cndmask_b32_e32 v11, v14, v22, vcc
	v_cndmask_b32_e32 v15, v15, v24, vcc
	v_cndmask_b32_e64 v14, v11, v13, s[4:5]
	v_cndmask_b32_e64 v11, v15, v11, s[4:5]
	v_cndmask_b32_e32 v15, v22, v18, vcc
	v_cndmask_b32_e64 v13, v13, v15, s[4:5]
	v_sub_u32_e32 v17, 32, v7
	v_cmp_eq_u32_e64 s[8:9], 0, v7
	v_cndmask_b32_e32 v7, v20, v16, vcc
	v_cndmask_b32_e64 v11, v11, v14, s[6:7]
	v_cndmask_b32_e64 v14, v14, v13, s[6:7]
	v_cndmask_b32_e64 v15, v15, v7, s[4:5]
	v_alignbit_b32 v19, v11, v14, v17
	v_cndmask_b32_e64 v13, v13, v15, s[6:7]
	v_cndmask_b32_e32 v12, v18, v12, vcc
	v_cndmask_b32_e64 v11, v19, v11, s[8:9]
	v_alignbit_b32 v16, v14, v13, v17
	v_cndmask_b32_e64 v7, v7, v12, s[4:5]
	v_cndmask_b32_e64 v14, v16, v14, s[8:9]
	v_bfe_u32 v20, v11, 29, 1
	v_cndmask_b32_e64 v7, v15, v7, s[6:7]
	v_alignbit_b32 v16, v11, v14, 30
	v_sub_u32_e32 v21, 0, v20
	v_alignbit_b32 v12, v13, v7, v17
	v_xor_b32_e32 v16, v16, v21
	v_cndmask_b32_e64 v12, v12, v13, s[8:9]
	v_alignbit_b32 v13, v14, v12, 30
	v_ffbh_u32_e32 v14, v16
	v_min_u32_e32 v14, 32, v14
	v_alignbit_b32 v7, v12, v7, 30
	v_xor_b32_e32 v13, v13, v21
	v_sub_u32_e32 v15, 31, v14
	v_xor_b32_e32 v7, v7, v21
	v_alignbit_b32 v16, v16, v13, v15
	v_alignbit_b32 v7, v13, v7, v15
	v_alignbit_b32 v12, v16, v7, 9
	v_ffbh_u32_e32 v13, v12
	v_min_u32_e32 v13, 32, v13
	v_lshrrev_b32_e32 v19, 29, v11
	v_not_b32_e32 v15, v13
	v_alignbit_b32 v7, v12, v7, v15
	v_lshlrev_b32_e32 v12, 31, v19
	v_or_b32_e32 v15, 0x33000000, v12
	v_add_lshl_u32 v13, v13, v14, 23
	v_lshrrev_b32_e32 v7, 9, v7
	v_sub_u32_e32 v13, v15, v13
	v_or_b32_e32 v12, 0.5, v12
	v_lshlrev_b32_e32 v14, 23, v14
	v_or_b32_e32 v7, v13, v7
	v_lshrrev_b32_e32 v13, 9, v16
	v_sub_u32_e32 v12, v12, v14
	v_or_b32_e32 v12, v13, v12
	s_mov_b32 s4, 0x3fc90fda
	v_mul_f32_e32 v13, 0x3fc90fda, v12
	v_fma_f32 v14, v12, s4, -v13
	v_fmamk_f32 v12, v12, 0x33a22168, v14
	v_fmac_f32_e32 v12, 0x3fc90fda, v7
	v_lshrrev_b32_e32 v11, 30, v11
	v_add_f32_e32 v7, v13, v12
	v_add_u32_e32 v11, v20, v11

; __device__ __forceinline__ unsigned f2bf(float f) { unsigned u = __float_as_uint(f); return (u + 0x7fffu + ((u >> 16) & 1u)) >> 16; }
; __device__ __forceinline__ void phase_carry(Frame& F, const Params& p) {
;     ...
;         } else {
;             for (int c = 7; c >= 0; --c) { const float sr = SC[c * 256], si = SC[c * 256 + 64]; const float nr = ar * hr - ai * hi + sr; hi = ar * hi + ai * hr + si; hr = nr; }
;             for (int n0 = 504; n0 >= 0; n0 -= 8) {
;                 float sr[8], si[8];
; #pragma unroll
;                 for (int u = 0; u < 8; ++u) { sr[u] = SB[(size_t)(n0 + u) * 256]; si[u] = SB[(size_t)(n0 + u) * 256 + 64]; }
; #pragma unroll
;                 for (int u = 7; u >= 0; --u) { X[(size_t)(n0 + u) * XK] = (bf16)f2bf(hr); X[(size_t)(n0 + u) * XK + 64] = (bf16)f2bf(hi);
;                     const float nr = ar * hr - ai * hi + sr[u]; hi = ar * hi + ai * hr + si[u]; hr = nr; }
;             }
.LBB0_798:
	v_mov_b32_e32 v4, v18
	v_mov_b32_e32 v5, v16
	v_mov_b32_e32 v2, v22
	v_mov_b32_e32 v3, v23
	s_branch .Lmy_s5_d1

; __device__ __forceinline__ unsigned f2bf(float f) { unsigned u = __float_as_uint(f); return (u + 0x7fffu + ((u >> 16) & 1u)) >> 16; }
; __device__ __forceinline__ void phase_carry(Frame& F, const Params& p) {
;     ...
;             for (int n0 = 0; n0 < 512; n0 += 8) {
;                 float sr[8], si[8];
; #pragma unroll
;                 for (int u = 0; u < 8; ++u) { sr[u] = SB[(size_t)(n0 + u) * 256]; si[u] = SB[(size_t)(n0 + u) * 256 + 64]; }
; #pragma unroll
;                 for (int u = 0; u < 8; ++u) { X[(size_t)(n0 + u) * XK] = (bf16)f2bf(hr); X[(size_t)(n0 + u) * XK + 64] = (bf16)f2bf(hi);
;                     const float nr = ar * hr - ai * hi + sr[u]; hi = ar * hi + ai * hr + si[u]; hr = nr; }
;             }
.LBB0_801:
	v_mov_b32_e32 v8, v2
	v_mov_b32_e32 v2, v4
	v_mov_b32_e32 v3, v5
	v_mov_b32_e32 v4, v8
	v_mov_b32_e32 v5, v6
	s_branch .Lmy_s5_d0
.Lmy_s5_d0:
	s_movk_i32 s13, 0x7fff
	s_mov_b32 s17, 0
	s_lshl_b32 s18, s17, 10
	s_add_u32 s4, s56, s18
	s_addc_u32 s5, s57, 0
	s_add_u32 s4, s4, 0x10000000
	s_addc_u32 s5, s5, 0
	s_mul_i32 s18, s17, 0x600
	s_add_u32 s8, s56, s18
	s_addc_u32 s9, s57, 0
	s_add_u32 s8, s8, 0x18000400
	s_addc_u32 s9, s9, 0
	s_add_u32 s10, s8, 0xc00
	s_addc_u32 s11, s9, 0
	global_load_dword v12, v4, s[4:5]
	global_load_dword v13, v4, s[4:5] offset:256
	global_load_dword v14, v4, s[4:5] offset:1024
	global_load_dword v15, v4, s[4:5] offset:1280
	global_load_dword v16, v4, s[4:5] offset:2048
	global_load_dword v17, v4, s[4:5] offset:2304
	global_load_dword v18, v4, s[4:5] offset:3072
	global_load_dword v19, v4, s[4:5] offset:3328
	s_add_u32 s4, s4, 0x1000
	s_addc_u32 s5, s5, 0
	global_load_dword v48, v4, s[4:5]
	global_load_dword v48, v4, s[4:5]
	global_load_dword v48, v4, s[4:5]
	global_load_dword v48, v4, s[4:5]
	global_load_dword v48, v4, s[4:5]
	global_load_dword v48, v4, s[4:5]
	global_load_dword v48, v4, s[4:5]
	global_load_dword v48, v4, s[4:5]
	global_load_dword v20, v4, s[4:5]
	global_load_dword v21, v4, s[4:5] offset:256
	global_load_dword v22, v4, s[4:5] offset:1024
	global_load_dword v23, v4, s[4:5] offset:1280
	global_load_dword v24, v4, s[4:5] offset:2048
	global_load_dword v25, v4, s[4:5] offset:2304
	global_load_dword v26, v4, s[4:5] offset:3072
	global_load_dword v27, v4, s[4:5] offset:3328
	s_add_u32 s4, s4, 0x1000
	s_addc_u32 s5, s5, 0
	global_load_dword v48, v4, s[4:5]
	global_load_dword v48, v4, s[4:5]
	global_load_dword v48, v4, s[4:5]
	global_load_dword v48, v4, s[4:5]
	global_load_dword v48, v4, s[4:5]
	global_load_dword v48, v4, s[4:5]
	global_load_dword v48, v4, s[4:5]
	global_load_dword v48, v4, s[4:5]
	global_load_dword v28, v4, s[4:5]
	global_load_dword v29, v4, s[4:5] offset:256
	global_load_dword v30, v4, s[4:5] offset:1024
	global_load_dword v31, v4, s[4:5] offset:1280
	global_load_dword v32, v4, s[4:5] offset:2048
	global_load_dword v33, v4, s[4:5] offset:2304
	global_load_dword v34, v4, s[4:5] offset:3072
	global_load_dword v35, v4, s[4:5] offset:3328
	s_add_u32 s4, s4, 0x1000
	s_addc_u32 s5, s5, 0
	global_load_dword v48, v4, s[4:5]
	global_load_dword v48, v4, s[4:5]
	global_load_dword v48, v4, s[4:5]
	global_load_dword v48, v4, s[4:5]
	global_load_dword v48, v4, s[4:5]
	global_load_dword v48, v4, s[4:5]
	global_load_dword v48, v4, s[4:5]
	global_load_dword v48, v4, s[4:5]
	s_mov_b32 s12, 32
.Lmy_s5b_d0:
	global_load_dword v36, v4, s[4:5]
	global_load_dword v37, v4, s[4:5] offset:256
	global_load_dword v38, v4, s[4:5] offset:1024
	global_load_dword v39, v4, s[4:5] offset:1280
	global_load_dword v40, v4, s[4:5] offset:2048
	global_load_dword v41, v4, s[4:5] offset:2304
	global_load_dword v42, v4, s[4:5] offset:3072
	global_load_dword v43, v4, s[4:5] offset:3328
	s_add_u32 s4, s4, 0x1000
	s_addc_u32 s5, s5, 0
	s_waitcnt vmcnt(48)
	v_bfe_u32 v44, v2, 16, 1
	v_bfe_u32 v45, v3, 16, 1
	v_add3_u32 v44, v2, v44, s13
	v_add3_u32 v45, v3, v45, s13
	global_store_short_d16_hi v5, v44, s[8:9]
	global_store_short_d16_hi v5, v45, s[8:9] offset:128
	v_fma_f32 v8, -v0, v3, v12
	v_fma_f32 v9, v1, v3, v13
	v_fma_f32 v47, v0, v2, v9
	v_fma_f32 v46, v1, v2, v8
	v_bfe_u32 v50, v46, 16, 1
	v_bfe_u32 v51, v47, 16, 1
	v_add3_u32 v50, v46, v50, s13
	v_add3_u32 v51, v47, v51, s13
	global_store_short_d16_hi v5, v50, s[8:9] offset:1536
	global_store_short_d16_hi v5, v51, s[8:9] offset:1664
	v_fma_f32 v8, -v0, v47, v14
	v_fma_f32 v9, v1, v47, v15
	v_fma_f32 v3, v0, v46, v9
	v_fma_f32 v2, v1, v46, v8
	v_bfe_u32 v44, v2, 16, 1
	v_bfe_u32 v45, v3, 16, 1
	v_add3_u32 v44, v2, v44, s13
	v_add3_u32 v45, v3, v45, s13
	global_store_short_d16_hi v5, v44, s[10:11]
	global_store_short_d16_hi v5, v45, s[10:11] offset:128
	v_fma_f32 v8, -v0, v3, v16
	v_fma_f32 v9, v1, v3, v17
	v_fma_f32 v47, v0, v2, v9
	v_fma_f32 v46, v1, v2, v8
	v_bfe_u32 v50, v46, 16, 1
	v_bfe_u32 v51, v47, 16, 1
	v_add3_u32 v50, v46, v50, s13
	v_add3_u32 v51, v47, v51, s13
	global_store_short_d16_hi v5, v50, s[10:11] offset:1536
	global_store_short_d16_hi v5, v51, s[10:11] offset:1664
	v_fma_f32 v8, -v0, v47, v18
	v_fma_f32 v9, v1, v47, v19
	v_fma_f32 v3, v0, v46, v9
	v_fma_f32 v2, v1, v46, v8
	s_add_u32 s8, s8, 0x1800
	s_addc_u32 s9, s9, 0
	s_add_u32 s10, s10, 0x1800
	s_addc_u32 s11, s11, 0
	global_load_dword v12, v4, s[4:5]
	global_load_dword v13, v4, s[4:5] offset:256
	global_load_dword v14, v4, s[4:5] offset:1024
	global_load_dword v15, v4, s[4:5] offset:1280
	global_load_dword v16, v4, s[4:5] offset:2048
	global_load_dword v17, v4, s[4:5] offset:2304
	global_load_dword v18, v4, s[4:5] offset:3072
	global_load_dword v19, v4, s[4:5] offset:3328
	s_add_u32 s4, s4, 0x1000
	s_addc_u32 s5, s5, 0
	s_waitcnt vmcnt(48)
; __device__ __forceinline__ unsigned f2bf(float f) { unsigned u = __float_as_uint(f); return (u + 0x7fffu + ((u >> 16) & 1u)) >> 16; }
; __device__ __forceinline__ void phase_carry(Frame& F, const Params& p) {
;     ...
;                 for (int u = 0; u < 8; ++u) { sr[u] = SB[(size_t)(n0 + u) * 256]; si[u] = SB[(size_t)(n0 + u) * 256 + 64]; }
; #pragma unroll
;                 for (int u = 0; u < 8; ++u) { X[(size_t)(n0 + u) * XK] = (bf16)f2bf(hr); X[(size_t)(n0 + u) * XK + 64] = (bf16)f2bf(hi);
;                     const float nr = ar * hr - ai * hi + sr[u]; hi = ar * hi + ai * hr + si[u]; hr = nr; }
	v_bfe_u32 v44, v2, 16, 1
	v_bfe_u32 v45, v3, 16, 1
	v_add3_u32 v44, v2, v44, s13
	v_add3_u32 v45, v3, v45, s13
	global_store_short_d16_hi v5, v44, s[8:9]
	global_store_short_d16_hi v5, v45, s[8:9] offset:128
	v_fma_f32 v8, -v0, v3, v20
	v_fma_f32 v9, v1, v3, v21
	v_fma_f32 v47, v0, v2, v9
	v_fma_f32 v46, v1, v2, v8
	v_bfe_u32 v50, v46, 16, 1
	v_bfe_u32 v51, v47, 16, 1
	v_add3_u32 v50, v46, v50, s13
	v_add3_u32 v51, v47, v51, s13
	global_store_short_d16_hi v5, v50, s[8:9] offset:1536
	global_store_short_d16_hi v5, v51, s[8:9] offset:1664
	v_fma_f32 v8, -v0, v47, v22
	v_fma_f32 v9, v1, v47, v23
	v_fma_f32 v3, v0, v46, v9
	v_fma_f32 v2, v1, v46, v8
	v_bfe_u32 v44, v2, 16, 1
	v_bfe_u32 v45, v3, 16, 1
	v_add3_u32 v44, v2, v44, s13
	v_add3_u32 v45, v3, v45, s13
	global_store_short_d16_hi v5, v44, s[10:11]
	global_store_short_d16_hi v5, v45, s[10:11] offset:128
	v_fma_f32 v8, -v0, v3, v24
	v_fma_f32 v9, v1, v3, v25
	v_fma_f32 v47, v0, v2, v9
	v_fma_f32 v46, v1, v2, v8
	v_bfe_u32 v50, v46, 16, 1
	v_bfe_u32 v51, v47, 16, 1
	v_add3_u32 v50, v46, v50, s13
	v_add3_u32 v51, v47, v51, s13
	global_store_short_d16_hi v5, v50, s[10:11] offset:1536
	global_store_short_d16_hi v5, v51, s[10:11] offset:1664
	v_fma_f32 v8, -v0, v47, v26
	v_fma_f32 v9, v1, v47, v27
	v_fma_f32 v3, v0, v46, v9
	v_fma_f32 v2, v1, v46, v8
	s_add_u32 s8, s8, 0x1800
	s_addc_u32 s9, s9, 0
	s_add_u32 s10, s10, 0x1800
	s_addc_u32 s11, s11, 0
	global_load_dword v20, v4, s[4:5]
	global_load_dword v21, v4, s[4:5] offset:256
	global_load_dword v22, v4, s[4:5] offset:1024
	global_load_dword v23, v4, s[4:5] offset:1280
	global_load_dword v24, v4, s[4:5] offset:2048
	global_load_dword v25, v4, s[4:5] offset:2304
	global_load_dword v26, v4, s[4:5] offset:3072
	global_load_dword v27, v4, s[4:5] offset:3328
	s_add_u32 s4, s4, 0x1000
	s_addc_u32 s5, s5, 0
	s_waitcnt vmcnt(48)
	v_bfe_u32 v44, v2, 16, 1
	v_bfe_u32 v45, v3, 16, 1
	v_add3_u32 v44, v2, v44, s13
	v_add3_u32 v45, v3, v45, s13
	global_store_short_d16_hi v5, v44, s[8:9]
	global_store_short_d16_hi v5, v45, s[8:9] offset:128
	v_fma_f32 v8, -v0, v3, v28
	v_fma_f32 v9, v1, v3, v29
	v_fma_f32 v47, v0, v2, v9
	v_fma_f32 v46, v1, v2, v8
	v_bfe_u32 v50, v46, 16, 1
	v_bfe_u32 v51, v47, 16, 1
	v_add3_u32 v50, v46, v50, s13
	v_add3_u32 v51, v47, v51, s13
	global_store_short_d16_hi v5, v50, s[8:9] offset:1536
	global_store_short_d16_hi v5, v51, s[8:9] offset:1664
	v_fma_f32 v8, -v0, v47, v30
	v_fma_f32 v9, v1, v47, v31
	v_fma_f32 v3, v0, v46, v9
	v_fma_f32 v2, v1, v46, v8
	v_bfe_u32 v44, v2, 16, 1
	v_bfe_u32 v45, v3, 16, 1
	v_add3_u32 v44, v2, v44, s13
	v_add3_u32 v45, v3, v45, s13
	global_store_short_d16_hi v5, v44, s[10:11]
	global_store_short_d16_hi v5, v45, s[10:11] offset:128
	v_fma_f32 v8, -v0, v3, v32
	v_fma_f32 v9, v1, v3, v33
	v_fma_f32 v47, v0, v2, v9
	v_fma_f32 v46, v1, v2, v8
	v_bfe_u32 v50, v46, 16, 1
	v_bfe_u32 v51, v47, 16, 1
	v_add3_u32 v50, v46, v50, s13
	v_add3_u32 v51, v47, v51, s13
	global_store_short_d16_hi v5, v50, s[10:11] offset:1536
	global_store_short_d16_hi v5, v51, s[10:11] offset:1664
	v_fma_f32 v8, -v0, v47, v34
	v_fma_f32 v9, v1, v47, v35
	v_fma_f32 v3, v0, v46, v9
	v_fma_f32 v2, v1, v46, v8
	s_add_u32 s8, s8, 0x1800
	s_addc_u32 s9, s9, 0
	s_add_u32 s10, s10, 0x1800
	s_addc_u32 s11, s11, 0
	global_load_dword v28, v4, s[4:5]
	global_load_dword v29, v4, s[4:5] offset:256
	global_load_dword v30, v4, s[4:5] offset:1024
	global_load_dword v31, v4, s[4:5] offset:1280
	global_load_dword v32, v4, s[4:5] offset:2048
	global_load_dword v33, v4, s[4:5] offset:2304
	global_load_dword v34, v4, s[4:5] offset:3072
	global_load_dword v35, v4, s[4:5] offset:3328
	s_add_u32 s4, s4, 0x1000
	s_addc_u32 s5, s5, 0
	s_waitcnt vmcnt(48)
	v_bfe_u32 v44, v2, 16, 1
	v_bfe_u32 v45, v3, 16, 1
	v_add3_u32 v44, v2, v44, s13
	v_add3_u32 v45, v3, v45, s13
	global_store_short_d16_hi v5, v44, s[8:9]
	global_store_short_d16_hi v5, v45, s[8:9] offset:128
	v_fma_f32 v8, -v0, v3, v36
	v_fma_f32 v9, v1, v3, v37
	v_fma_f32 v47, v0, v2, v9
	v_fma_f32 v46, v1, v2, v8
	v_bfe_u32 v50, v46, 16, 1
	v_bfe_u32 v51, v47, 16, 1
	v_add3_u32 v50, v46, v50, s13
	v_add3_u32 v51, v47, v51, s13
	global_store_short_d16_hi v5, v50, s[8:9] offset:1536
	global_store_short_d16_hi v5, v51, s[8:9] offset:1664
	v_fma_f32 v8, -v0, v47, v38
	v_fma_f32 v9, v1, v47, v39
	v_fma_f32 v3, v0, v46, v9
	v_fma_f32 v2, v1, v46, v8
	v_bfe_u32 v44, v2, 16, 1
	v_bfe_u32 v45, v3, 16, 1
	v_add3_u32 v44, v2, v44, s13
	v_add3_u32 v45, v3, v45, s13
	global_store_short_d16_hi v5, v44, s[10:11]
	global_store_short_d16_hi v5, v45, s[10:11] offset:128
	v_fma_f32 v8, -v0, v3, v40
	v_fma_f32 v9, v1, v3, v41
	v_fma_f32 v47, v0, v2, v9
	v_fma_f32 v46, v1, v2, v8
	v_bfe_u32 v50, v46, 16, 1
	v_bfe_u32 v51, v47, 16, 1
	v_add3_u32 v50, v46, v50, s13
	v_add3_u32 v51, v47, v51, s13
	global_store_short_d16_hi v5, v50, s[10:11] offset:1536
	global_store_short_d16_hi v5, v51, s[10:11] offset:1664
	v_fma_f32 v8, -v0, v47, v42
	v_fma_f32 v9, v1, v47, v43
	v_fma_f32 v3, v0, v46, v9
	v_fma_f32 v2, v1, v46, v8
	s_add_u32 s8, s8, 0x1800
	s_addc_u32 s9, s9, 0
	s_add_u32 s10, s10, 0x1800
	s_addc_u32 s11, s11, 0
	s_sub_u32 s12, s12, 1
	s_cmp_lg_u32 s12, 0
	s_cbranch_scc1 .Lmy_s5b_d0
	s_branch .Lmy_after_s5
; __device__ __forceinline__ unsigned f2bf(float f) { unsigned u = __float_as_uint(f); return (u + 0x7fffu + ((u >> 16) & 1u)) >> 16; }
; __device__ __forceinline__ void phase_carry(Frame& F, const Params& p) {
;     ...
;             for (int n0 = 504; n0 >= 0; n0 -= 8) {
;                 float sr[8], si[8];
; #pragma unroll
;                 for (int u = 0; u < 8; ++u) { sr[u] = SB[(size_t)(n0 + u) * 256]; si[u] = SB[(size_t)(n0 + u) * 256 + 64]; }
; #pragma unroll
;                 for (int u = 7; u >= 0; --u) { X[(size_t)(n0 + u) * XK] = (bf16)f2bf(hr); X[(size_t)(n0 + u) * XK + 64] = (bf16)f2bf(hi);
;                     const float nr = ar * hr - ai * hi + sr[u]; hi = ar * hi + ai * hr + si[u]; hr = nr; }
.Lmy_s5_d1:
	s_movk_i32 s13, 0x7fff
	s_mov_b32 s17, 0x1fc
	s_lshl_b32 s18, s17, 10
	s_add_u32 s4, s56, s18
	s_addc_u32 s5, s57, 0
	s_add_u32 s4, s4, 0x10000000
	s_addc_u32 s5, s5, 0
	s_mul_i32 s18, s17, 0x600
	s_add_u32 s8, s56, s18
	s_addc_u32 s9, s57, 0
	s_add_u32 s8, s8, 0x18000400
	s_addc_u32 s9, s9, 0
	s_add_u32 s10, s8, 0xc00
	s_addc_u32 s11, s9, 0
	global_load_dword v12, v4, s[4:5] offset:3072
	global_load_dword v13, v4, s[4:5] offset:3328
	global_load_dword v14, v4, s[4:5] offset:2048
	global_load_dword v15, v4, s[4:5] offset:2304
	global_load_dword v16, v4, s[4:5] offset:1024
	global_load_dword v17, v4, s[4:5] offset:1280
	global_load_dword v18, v4, s[4:5]
	global_load_dword v19, v4, s[4:5] offset:256
	s_add_u32 s4, s4, 0xfffff000
	s_addc_u32 s5, s5, -1
	global_load_dword v48, v4, s[4:5]
	global_load_dword v48, v4, s[4:5]
	global_load_dword v48, v4, s[4:5]
	global_load_dword v48, v4, s[4:5]
	global_load_dword v48, v4, s[4:5]
	global_load_dword v48, v4, s[4:5]
	global_load_dword v48, v4, s[4:5]
	global_load_dword v48, v4, s[4:5]
	global_load_dword v20, v4, s[4:5] offset:3072
	global_load_dword v21, v4, s[4:5] offset:3328
	global_load_dword v22, v4, s[4:5] offset:2048
	global_load_dword v23, v4, s[4:5] offset:2304
	global_load_dword v24, v4, s[4:5] offset:1024
	global_load_dword v25, v4, s[4:5] offset:1280
	global_load_dword v26, v4, s[4:5]
	global_load_dword v27, v4, s[4:5] offset:256
	s_add_u32 s4, s4, 0xfffff000
	s_addc_u32 s5, s5, -1
	global_load_dword v48, v4, s[4:5]
	global_load_dword v48, v4, s[4:5]
	global_load_dword v48, v4, s[4:5]
	global_load_dword v48, v4, s[4:5]
	global_load_dword v48, v4, s[4:5]
	global_load_dword v48, v4, s[4:5]
	global_load_dword v48, v4, s[4:5]
	global_load_dword v48, v4, s[4:5]
	global_load_dword v28, v4, s[4:5] offset:3072
	global_load_dword v29, v4, s[4:5] offset:3328
	global_load_dword v30, v4, s[4:5] offset:2048
	global_load_dword v31, v4, s[4:5] offset:2304
	global_load_dword v32, v4, s[4:5] offset:1024
	global_load_dword v33, v4, s[4:5] offset:1280
	global_load_dword v34, v4, s[4:5]
	global_load_dword v35, v4, s[4:5] offset:256
	s_add_u32 s4, s4, 0xfffff000
	s_addc_u32 s5, s5, -1
	global_load_dword v48, v4, s[4:5]
	global_load_dword v48, v4, s[4:5]
	global_load_dword v48, v4, s[4:5]
	global_load_dword v48, v4, s[4:5]
	global_load_dword v48, v4, s[4:5]
	global_load_dword v48, v4, s[4:5]
	global_load_dword v48, v4, s[4:5]
	global_load_dword v48, v4, s[4:5]
	s_mov_b32 s12, 32
.Lmy_s5b_d1:
	global_load_dword v36, v4, s[4:5] offset:3072
	global_load_dword v37, v4, s[4:5] offset:3328
	global_load_dword v38, v4, s[4:5] offset:2048
	global_load_dword v39, v4, s[4:5] offset:2304
	global_load_dword v40, v4, s[4:5] offset:1024
	global_load_dword v41, v4, s[4:5] offset:1280
	global_load_dword v42, v4, s[4:5]
	global_load_dword v43, v4, s[4:5] offset:256
	s_add_u32 s4, s4, 0xfffff000
	s_addc_u32 s5, s5, -1
	s_waitcnt vmcnt(48)
	v_bfe_u32 v44, v2, 16, 1
	v_bfe_u32 v45, v3, 16, 1
	v_add3_u32 v44, v2, v44, s13
	v_add3_u32 v45, v3, v45, s13
	global_store_short_d16_hi v5, v44, s[10:11] offset:1536
	global_store_short_d16_hi v5, v45, s[10:11] offset:1664
	v_fma_f32 v8, -v0, v3, v12
	v_fma_f32 v9, v1, v3, v13
	v_fma_f32 v47, v0, v2, v9
	v_fma_f32 v46, v1, v2, v8
	v_bfe_u32 v50, v46, 16, 1
	v_bfe_u32 v51, v47, 16, 1
	v_add3_u32 v50, v46, v50, s13
	v_add3_u32 v51, v47, v51, s13
	global_store_short_d16_hi v5, v50, s[10:11]
	global_store_short_d16_hi v5, v51, s[10:11] offset:128
	v_fma_f32 v8, -v0, v47, v14
	v_fma_f32 v9, v1, v47, v15
	v_fma_f32 v3, v0, v46, v9
	v_fma_f32 v2, v1, v46, v8
	v_bfe_u32 v44, v2, 16, 1
	v_bfe_u32 v45, v3, 16, 1
	v_add3_u32 v44, v2, v44, s13
	v_add3_u32 v45, v3, v45, s13
	global_store_short_d16_hi v5, v44, s[8:9] offset:1536
	global_store_short_d16_hi v5, v45, s[8:9] offset:1664
	v_fma_f32 v8, -v0, v3, v16
	v_fma_f32 v9, v1, v3, v17
	v_fma_f32 v47, v0, v2, v9
	v_fma_f32 v46, v1, v2, v8
	v_bfe_u32 v50, v46, 16, 1
	v_bfe_u32 v51, v47, 16, 1
	v_add3_u32 v50, v46, v50, s13
	v_add3_u32 v51, v47, v51, s13
	global_store_short_d16_hi v5, v50, s[8:9]
	global_store_short_d16_hi v5, v51, s[8:9] offset:128
	v_fma_f32 v8, -v0, v47, v18
	v_fma_f32 v9, v1, v47, v19
	v_fma_f32 v3, v0, v46, v9
	v_fma_f32 v2, v1, v46, v8
	s_add_u32 s8, s8, 0xffffe800
	s_addc_u32 s9, s9, -1
	s_add_u32 s10, s10, 0xffffe800
	s_addc_u32 s11, s11, -1
	global_load_dword v12, v4, s[4:5] offset:3072
	global_load_dword v13, v4, s[4:5] offset:3328
	global_load_dword v14, v4, s[4:5] offset:2048
	global_load_dword v15, v4, s[4:5] offset:2304
	global_load_dword v16, v4, s[4:5] offset:1024
	global_load_dword v17, v4, s[4:5] offset:1280
	global_load_dword v18, v4, s[4:5]
	global_load_dword v19, v4, s[4:5] offset:256
	s_add_u32 s4, s4, 0xfffff000
	s_addc_u32 s5, s5, -1
	s_waitcnt vmcnt(48)
; __device__ __forceinline__ unsigned f2bf(float f) { unsigned u = __float_as_uint(f); return (u + 0x7fffu + ((u >> 16) & 1u)) >> 16; }
; __device__ __forceinline__ void phase_carry(Frame& F, const Params& p) {
;     ...
;             for (int n0 = 504; n0 >= 0; n0 -= 8) {
;                 float sr[8], si[8];
; #pragma unroll
;                 for (int u = 0; u < 8; ++u) { sr[u] = SB[(size_t)(n0 + u) * 256]; si[u] = SB[(size_t)(n0 + u) * 256 + 64]; }
; #pragma unroll
;                 for (int u = 7; u >= 0; --u) { X[(size_t)(n0 + u) * XK] = (bf16)f2bf(hr); X[(size_t)(n0 + u) * XK + 64] = (bf16)f2bf(hi);
;                     const float nr = ar * hr - ai * hi + sr[u]; hi = ar * hi + ai * hr + si[u]; hr = nr; }
	v_bfe_u32 v44, v2, 16, 1
	v_bfe_u32 v45, v3, 16, 1
	v_add3_u32 v44, v2, v44, s13
	v_add3_u32 v45, v3, v45, s13
	global_store_short_d16_hi v5, v44, s[10:11] offset:1536
	global_store_short_d16_hi v5, v45, s[10:11] offset:1664
	v_fma_f32 v8, -v0, v3, v20
	v_fma_f32 v9, v1, v3, v21
	v_fma_f32 v47, v0, v2, v9
	v_fma_f32 v46, v1, v2, v8
	v_bfe_u32 v50, v46, 16, 1
	v_bfe_u32 v51, v47, 16, 1
	v_add3_u32 v50, v46, v50, s13
	v_add3_u32 v51, v47, v51, s13
	global_store_short_d16_hi v5, v50, s[10:11]
	global_store_short_d16_hi v5, v51, s[10:11] offset:128
	v_fma_f32 v8, -v0, v47, v22
	v_fma_f32 v9, v1, v47, v23
	v_fma_f32 v3, v0, v46, v9
	v_fma_f32 v2, v1, v46, v8
	v_bfe_u32 v44, v2, 16, 1
	v_bfe_u32 v45, v3, 16, 1
	v_add3_u32 v44, v2, v44, s13
	v_add3_u32 v45, v3, v45, s13
	global_store_short_d16_hi v5, v44, s[8:9] offset:1536
	global_store_short_d16_hi v5, v45, s[8:9] offset:1664
	v_fma_f32 v8, -v0, v3, v24
	v_fma_f32 v9, v1, v3, v25
	v_fma_f32 v47, v0, v2, v9
	v_fma_f32 v46, v1, v2, v8
	v_bfe_u32 v50, v46, 16, 1
	v_bfe_u32 v51, v47, 16, 1
	v_add3_u32 v50, v46, v50, s13
	v_add3_u32 v51, v47, v51, s13
	global_store_short_d16_hi v5, v50, s[8:9]
	global_store_short_d16_hi v5, v51, s[8:9] offset:128
	v_fma_f32 v8, -v0, v47, v26
	v_fma_f32 v9, v1, v47, v27
	v_fma_f32 v3, v0, v46, v9
	v_fma_f32 v2, v1, v46, v8
	s_add_u32 s8, s8, 0xffffe800
	s_addc_u32 s9, s9, -1
	s_add_u32 s10, s10, 0xffffe800
	s_addc_u32 s11, s11, -1
	global_load_dword v20, v4, s[4:5] offset:3072
	global_load_dword v21, v4, s[4:5] offset:3328
	global_load_dword v22, v4, s[4:5] offset:2048
	global_load_dword v23, v4, s[4:5] offset:2304
	global_load_dword v24, v4, s[4:5] offset:1024
	global_load_dword v25, v4, s[4:5] offset:1280
	global_load_dword v26, v4, s[4:5]
	global_load_dword v27, v4, s[4:5] offset:256
	s_add_u32 s4, s4, 0xfffff000
	s_addc_u32 s5, s5, -1
	s_waitcnt vmcnt(48)
	v_bfe_u32 v44, v2, 16, 1
	v_bfe_u32 v45, v3, 16, 1
	v_add3_u32 v44, v2, v44, s13
	v_add3_u32 v45, v3, v45, s13
	global_store_short_d16_hi v5, v44, s[10:11] offset:1536
	global_store_short_d16_hi v5, v45, s[10:11] offset:1664
	v_fma_f32 v8, -v0, v3, v28
	v_fma_f32 v9, v1, v3, v29
	v_fma_f32 v47, v0, v2, v9
	v_fma_f32 v46, v1, v2, v8
	v_bfe_u32 v50, v46, 16, 1
	v_bfe_u32 v51, v47, 16, 1
	v_add3_u32 v50, v46, v50, s13
	v_add3_u32 v51, v47, v51, s13
	global_store_short_d16_hi v5, v50, s[10:11]
	global_store_short_d16_hi v5, v51, s[10:11] offset:128
	v_fma_f32 v8, -v0, v47, v30
	v_fma_f32 v9, v1, v47, v31
	v_fma_f32 v3, v0, v46, v9
	v_fma_f32 v2, v1, v46, v8
	v_bfe_u32 v44, v2, 16, 1
	v_bfe_u32 v45, v3, 16, 1
	v_add3_u32 v44, v2, v44, s13
	v_add3_u32 v45, v3, v45, s13
	global_store_short_d16_hi v5, v44, s[8:9] offset:1536
	global_store_short_d16_hi v5, v45, s[8:9] offset:1664
	v_fma_f32 v8, -v0, v3, v32
	v_fma_f32 v9, v1, v3, v33
	v_fma_f32 v47, v0, v2, v9
	v_fma_f32 v46, v1, v2, v8
	v_bfe_u32 v50, v46, 16, 1
	v_bfe_u32 v51, v47, 16, 1
	v_add3_u32 v50, v46, v50, s13
	v_add3_u32 v51, v47, v51, s13
	global_store_short_d16_hi v5, v50, s[8:9]
	global_store_short_d16_hi v5, v51, s[8:9] offset:128
	v_fma_f32 v8, -v0, v47, v34
	v_fma_f32 v9, v1, v47, v35
	v_fma_f32 v3, v0, v46, v9
	v_fma_f32 v2, v1, v46, v8
	s_add_u32 s8, s8, 0xffffe800
	s_addc_u32 s9, s9, -1
	s_add_u32 s10, s10, 0xffffe800
	s_addc_u32 s11, s11, -1
	global_load_dword v28, v4, s[4:5] offset:3072
	global_load_dword v29, v4, s[4:5] offset:3328
	global_load_dword v30, v4, s[4:5] offset:2048
	global_load_dword v31, v4, s[4:5] offset:2304
	global_load_dword v32, v4, s[4:5] offset:1024
	global_load_dword v33, v4, s[4:5] offset:1280
	global_load_dword v34, v4, s[4:5]
	global_load_dword v35, v4, s[4:5] offset:256
	s_add_u32 s4, s4, 0xfffff000
	s_addc_u32 s5, s5, -1
	s_waitcnt vmcnt(48)
	v_bfe_u32 v44, v2, 16, 1
	v_bfe_u32 v45, v3, 16, 1
	v_add3_u32 v44, v2, v44, s13
	v_add3_u32 v45, v3, v45, s13
	global_store_short_d16_hi v5, v44, s[10:11] offset:1536
	global_store_short_d16_hi v5, v45, s[10:11] offset:1664
	v_fma_f32 v8, -v0, v3, v36
	v_fma_f32 v9, v1, v3, v37
	v_fma_f32 v47, v0, v2, v9
	v_fma_f32 v46, v1, v2, v8
	v_bfe_u32 v50, v46, 16, 1
	v_bfe_u32 v51, v47, 16, 1
	v_add3_u32 v50, v46, v50, s13
	v_add3_u32 v51, v47, v51, s13
	global_store_short_d16_hi v5, v50, s[10:11]
	global_store_short_d16_hi v5, v51, s[10:11] offset:128
	v_fma_f32 v8, -v0, v47, v38
	v_fma_f32 v9, v1, v47, v39
	v_fma_f32 v3, v0, v46, v9
	v_fma_f32 v2, v1, v46, v8
	v_bfe_u32 v44, v2, 16, 1
	v_bfe_u32 v45, v3, 16, 1
	v_add3_u32 v44, v2, v44, s13
	v_add3_u32 v45, v3, v45, s13
	global_store_short_d16_hi v5, v44, s[8:9] offset:1536
	global_store_short_d16_hi v5, v45, s[8:9] offset:1664
	v_fma_f32 v8, -v0, v3, v40
	v_fma_f32 v9, v1, v3, v41
	v_fma_f32 v47, v0, v2, v9
	v_fma_f32 v46, v1, v2, v8
	v_bfe_u32 v50, v46, 16, 1
	v_bfe_u32 v51, v47, 16, 1
	v_add3_u32 v50, v46, v50, s13
	v_add3_u32 v51, v47, v51, s13
	global_store_short_d16_hi v5, v50, s[8:9]
	global_store_short_d16_hi v5, v51, s[8:9] offset:128
	v_fma_f32 v8, -v0, v47, v42
	v_fma_f32 v9, v1, v47, v43
	v_fma_f32 v3, v0, v46, v9
	v_fma_f32 v2, v1, v46, v8
	s_add_u32 s8, s8, 0xffffe800
	s_addc_u32 s9, s9, -1
	s_add_u32 s10, s10, 0xffffe800
	s_addc_u32 s11, s11, -1
	s_sub_u32 s12, s12, 1
	s_cmp_lg_u32 s12, 0
	s_cbranch_scc1 .Lmy_s5b_d1
	s_branch .Lmy_after_s5
.Lmy_after_s5:
	s_waitcnt vmcnt(0)
	s_mov_b64 exec, -1
	s_branch .LBB0_770
